# grid-barrier poll back-off: s_sleep 1 -> 3 in the two generation-flag spin loops
# speedup vs baseline: 1.0091x; 1.0091x over previous
.LBB0_1296:
	s_and_b32 s26, s0, 0xff
	s_mov_b64 s[24:25], -1
	s_cmp_lg_u32 s26, 0
	s_mov_b64 s[40:41], -1
	s_sleep 3
	s_cbranch_scc0 .LBB0_1299
	s_and_b64 vcc, exec, s[40:41]
	s_cbranch_vccz .LBB0_1295
